# no L2 write-back at the three grid barriers that only order a buffer re-use (down->qkv, mixout->wq, wo->gu2): their consumers read XCD-local data
# baseline (speedup 1.0000x reference)
; __device__ __forceinline__ unsigned xb_add(unsigned* p, unsigned v) { return __hip_atomic_fetch_add(p, v, __ATOMIC_RELAXED, __HIP_MEMORY_SCOPE_AGENT); }
; __device__ __forceinline__ void xcd_barrier(const XcdBarrier& b) {
;     ...
;         const unsigned old = xb_add(&bar[XB_XSUB(b.x)], 1u);
;         const unsigned gen = old / nloc;
;         if (old + 1u == (gen + 1u) * nloc) {
;             __builtin_amdgcn_fence(__ATOMIC_RELEASE, "agent");
;             asm volatile("s_waitcnt vmcnt(0)" ::: "memory");
;             const unsigned og = xb_add(&bar[XB_TOP], 1u);
.LBB0_296:
	s_andn2_saveexec_b64 s[2:3], s[2:3]
	s_cbranch_execz .LBB0_314
	s_mov_b64 s[2:3], exec
	s_waitcnt lgkmcnt(0)
	s_waitcnt vmcnt(0)
	v_mbcnt_lo_u32_b32 v0, s2, 0
	v_mbcnt_hi_u32_b32 v0, s3, v0
	v_cmp_eq_u32_e32 vcc, 0, v0
	s_and_saveexec_b64 s[4:5], vcc
	s_cbranch_execz .LBB0_299
	s_bcnt1_i32_b64 s2, s[2:3]
	v_mov_b32_e32 v3, s2
	v_readlane_b32 s2, v253, 52
	v_readlane_b32 s3, v253, 53
	s_nop 4
	global_atomic_add v3, v1, v3, s[2:3] sc0
